# v46 + phase-0 memory-rmsnorm loop: all 4 row loads and 4 gain loads issued together at loop top with counted vmcnt; gain reloads replaced by v_mov
# baseline (speedup 1.0000x reference)
.LBB0_498:
	global_load_dwordx4 v[10:13], v[22:23], off offset:-2048
	global_load_dwordx4 v[2:5], v[22:23], off offset:-1024
	global_load_dwordx4 v[14:17], v[22:23], off
	global_load_dwordx4 v[6:9], v[22:23], off offset:1024
	global_load_dwordx4 v[72:75], v[20:21], off
	global_load_dwordx4 v[80:83], v[20:21], off offset:1024
	global_load_dwordx4 v[84:87], v[20:21], off offset:2048
	global_load_dwordx4 v[88:91], v[20:21], off offset:3072
	v_add_u32_e32 v18, s10, v18
	s_movk_i32 s1, 0x3ff
	s_waitcnt vmcnt(7)
	v_mov_b32_e32 v36, v11
	s_waitcnt vmcnt(6)
	v_mov_b32_e32 v37, v3
	v_mov_b32_e32 v34, v10
	v_mov_b32_e32 v35, v2
	v_pk_mul_f32 v[36:37], v[36:37], v[36:37]
	s_nop 0
	v_pk_fma_f32 v[34:35], v[34:35], v[34:35], v[36:37]
	v_mov_b32_e32 v36, v12
	v_mov_b32_e32 v37, v4
	v_pk_fma_f32 v[34:35], v[36:37], v[36:37], v[34:35]
	v_mov_b32_e32 v36, v13
	v_mov_b32_e32 v37, v5
	v_pk_fma_f32 v[32:33], v[36:37], v[36:37], v[34:35]
	s_nop 0
	v_add_f32_e32 v0, v32, v33
	v_lshl_add_u64 v[22:23], v[22:23], 0, s[12:13]
	s_waitcnt vmcnt(5)
	v_mov_b32_e32 v36, v15
	s_waitcnt vmcnt(4)
	v_mov_b32_e32 v37, v7
	v_mov_b32_e32 v34, v14
	v_mov_b32_e32 v35, v6
	v_pk_mul_f32 v[36:37], v[36:37], v[36:37]
	s_nop 0
	v_pk_fma_f32 v[34:35], v[34:35], v[34:35], v[36:37]
	v_mov_b32_e32 v36, v16
	v_mov_b32_e32 v37, v8
	v_pk_fma_f32 v[34:35], v[36:37], v[36:37], v[34:35]
	v_mov_b32_e32 v36, v17
	v_mov_b32_e32 v37, v9
	v_pk_fma_f32 v[34:35], v[36:37], v[36:37], v[34:35]
	s_nop 0
	v_add_f32_e32 v0, v0, v34
	v_add_f32_e32 v0, v0, v35
	ds_bpermute_b32 v19, v26, v0
	s_waitcnt lgkmcnt(0)
	v_add_f32_e32 v0, v0, v19
	ds_bpermute_b32 v19, v27, v0
	s_waitcnt lgkmcnt(0)
	v_add_f32_e32 v0, v0, v19
	ds_bpermute_b32 v19, v28, v0
	s_waitcnt lgkmcnt(0)
	v_add_f32_e32 v0, v0, v19
	ds_bpermute_b32 v19, v29, v0
	s_waitcnt lgkmcnt(0)
	v_add_f32_e32 v0, v0, v19
	ds_bpermute_b32 v19, v30, v0
	s_waitcnt lgkmcnt(0)
	v_add_f32_e32 v0, v0, v19
	ds_bpermute_b32 v19, v31, v0
	s_waitcnt lgkmcnt(0)
	v_add_f32_e32 v0, v0, v19
	v_fmamk_f32 v0, v0, 0x3a800000, v244
	v_cmp_gt_f32_e32 vcc, s33, v0
	v_mul_f32_e32 v19, 0x4b800000, v0
	s_nop 0
	v_cndmask_b32_e32 v0, v0, v19, vcc
	v_rsq_f32_e32 v0, v0
	s_nop 0
	v_mul_f32_e32 v19, 0x45800000, v0
	v_cndmask_b32_e32 v0, v0, v19, vcc
	v_pk_mul_f32 v[10:11], v[10:11], v[0:1] op_sel_hi:[1,0]
	v_pk_mul_f32 v[12:13], v[12:13], v[0:1] op_sel_hi:[1,0]
	v_pk_mul_f32 v[2:3], v[2:3], v[0:1] op_sel_hi:[1,0]
	v_pk_mul_f32 v[4:5], v[4:5], v[0:1] op_sel_hi:[1,0]
	v_pk_mul_f32 v[6:7], v[6:7], v[0:1] op_sel_hi:[1,0]
	v_cmp_lt_i32_e32 vcc, s1, v18
	s_or_b64 s[16:17], vcc, s[16:17]
	s_waitcnt vmcnt(0)
	v_pk_mul_f32 v[10:11], v[72:73], v[10:11]
	v_pk_mul_f32 v[12:13], v[74:75], v[12:13]
	v_cvt_pk_bf16_f32 v10, v10, v11
	v_cvt_pk_bf16_f32 v11, v12, v13
	global_store_dwordx2 v[24:25], v[10:11], off offset:-1024
	s_nop 1
	v_mov_b32_e32 v10, v80
	v_mov_b32_e32 v11, v81
	v_mov_b32_e32 v12, v82
	v_mov_b32_e32 v13, v83
	v_pk_mul_f32 v[2:3], v[10:11], v[2:3]
	v_pk_mul_f32 v[4:5], v[12:13], v[4:5]
	v_cvt_pk_bf16_f32 v2, v2, v3
	v_cvt_pk_bf16_f32 v3, v4, v5
	global_store_dwordx2 v[24:25], v[2:3], off offset:-512
	s_nop 1
	v_mov_b32_e32 v2, v84
	v_mov_b32_e32 v3, v85
	v_mov_b32_e32 v4, v86
	v_mov_b32_e32 v5, v87
	v_pk_mul_f32 v[10:11], v[14:15], v[0:1] op_sel_hi:[1,0]
	v_pk_mul_f32 v[2:3], v[2:3], v[10:11]
	v_pk_mul_f32 v[10:11], v[16:17], v[0:1] op_sel_hi:[1,0]
	v_cvt_pk_bf16_f32 v2, v2, v3
	v_pk_mul_f32 v[4:5], v[4:5], v[10:11]
	s_nop 0
	v_cvt_pk_bf16_f32 v3, v4, v5
	global_store_dwordx2 v[24:25], v[2:3], off
	s_nop 1
	v_mov_b32_e32 v2, v88
	v_mov_b32_e32 v3, v89
	v_mov_b32_e32 v4, v90
	v_mov_b32_e32 v5, v91
	v_pk_mul_f32 v[2:3], v[2:3], v[6:7]
	v_pk_mul_f32 v[6:7], v[8:9], v[0:1] op_sel_hi:[1,0]
	v_cvt_pk_bf16_f32 v2, v2, v3
	v_pk_mul_f32 v[4:5], v[4:5], v[6:7]
	s_nop 0
	v_cvt_pk_bf16_f32 v3, v4, v5
	global_store_dwordx2 v[24:25], v[2:3], off offset:512
	v_lshl_add_u64 v[24:25], v[24:25], 0, s[14:15]
	s_andn2_b64 exec, exec, s[16:17]
	s_cbranch_execnz .LBB0_498
	s_branch .LBB0_495
